# post_z rope-k slab: 31 serialized rope loads issued up front into free VGPR pairs, counted vmcnt
# baseline (speedup 1.0000x reference)
; DI void post_z(const Params& p, int layer) {
;     ...
;   for (int item = gw; item < 1024 * 36; item += nw) {
;     const int tc = item / 36, slab = item - tc * 36;
;     const int tok0 = tc * 32;
;     const int b = tok0 >> 13, spos = tok0 & 8191;
;     bf16_t* zr = z + (size_t)tok0 * ZS;
;     if (slab >= 32) {
;       const int s4 = slab - 32, kv = s4 >> 1, gi = s4 & 1;
;       const int colbase = (kv ? C_VC : C_KC) + gi * 64;
;       bf16_t* dst = (bf16_t*)(p.ws + O_KVD) + ((size_t)((kv * 8 + b * 2 + gi) * SEQ + spos)) * 64 + lane;
;       bf16_t u[32];
; #pragma unroll
;       for (int i = 0; i < 32; ++i) u[i] = zr[(size_t)i * ZS + colbase + lane];
; #pragma unroll
;       for (int i = 0; i < 32; ++i) dst[i * 64] = u[i];
;     } else if (slab < 12) {
;       int colbase; const float* g; float sc;
;       if (slab < 8) { colbase = C_Q + slab * 64; g = qn; sc = 0.125f; }
;       else if (slab < 10) { colbase = C_KS + (slab - 8) * 64; g = kn; sc = 1.f; }
;       else { colbase = C_KW + (slab - 10) * 64; g = kn; sc = 1.f; }
;       const float gv = g[lane] * sc;
;       float v[32];
; #pragma unroll
;       for (int i = 0; i < 32; ++i) v[i] = bf2f(zr[(size_t)i * ZS + colbase + lane]);
; #pragma unroll
;       for (int i = 0; i < 32; ++i) {
;         float ss = wave_sum(v[i] * v[i], lane);
;         float rs = rsqrtf(ss * (1.f / 64.f) + 1e-6f);
;         zr[(size_t)i * ZS + colbase + lane] = f2bf(v[i] * rs * gv);
;       }
;     } else if (slab < 16 || slab >= 24) {
;     ...
;       const int h = slab - 20;
;       const int colbase = C_RK + h * 128;
;       const float lg2 = log2f(1.f - exp2f(-5.f - (float)h));
;       float x1[32], x2[32];
; #pragma unroll
;       for (int i = 0; i < 32; ++i) {
;         const bf16_t* p1 = zr + (size_t)i * ZS + colbase + lane;
;         x1[i] = bf2f(p1[0]);
;         x2[i] = bf2f(p1[64]);
;       }
;       unsigned u1[32], u2[32];
; #pragma unroll
;       for (int i = 0; i < 32; ++i) {
;         bf16_t* p1 = zr + (size_t)i * ZS + colbase + lane;
;         float2 cs = rope[(spos + i) * 64 + lane];
;         float o1 = (x1[i] * cs.x - x2[i] * cs.y) * 0.08838834764831845f;
;         float o2 = (x1[i] * cs.y + x2[i] * cs.x) * 0.08838834764831845f;
;         p1[0] = f2bf(o1);
;         p1[64] = f2bf(o2);
;         float zeta = exp2f(lg2 * (float)(127 - ((spos + i) & 127)));
.LBB0_188:
	s_mov_b32 s0, 0x38e38e39
	v_mul_hi_i32 v0, v30, s0
	v_lshrrev_b32_e32 v2, 31, v0
	v_ashrrev_i32_e32 v0, 3, v0
	v_add_u32_e32 v43, v0, v2
	s_movk_i32 s0, 0xffdc
	v_mad_u64_u32 v[2:3], s[0:1], v43, s0, v[30:31]
	v_lshlrev_b32_e32 v45, 5, v43
	v_mov_b64_e32 v[4:5], s[16:17]
	v_ashrrev_i32_e32 v50, 8, v43
	v_and_b32_e32 v42, 0x1fe0, v45
	v_mad_i64_i32 v[6:7], s[0:1], v45, s35, v[4:5]
	v_cmp_gt_i32_e32 vcc, 32, v2
	s_and_saveexec_b64 s[0:1], vcc
	s_xor_b64 s[44:45], exec, s[0:1]
	s_cbranch_execz .LBB0_214
	v_cmp_lt_i32_e32 vcc, 11, v2
	s_and_saveexec_b64 s[0:1], vcc
	s_xor_b64 s[2:3], exec, s[0:1]
	s_cbranch_execz .LBB0_203
	v_subrev_u32_e32 v0, 24, v2
	v_cmp_lt_u32_e32 vcc, -9, v0
	s_and_saveexec_b64 s[0:1], vcc
	s_xor_b64 s[46:47], exec, s[0:1]
	s_cbranch_execz .LBB0_196
	v_lshlrev_b32_e32 v0, 3, v32
	v_cmp_lt_u32_e32 vcc, 19, v2
	v_lshl_or_b32 v4, v42, 9, v0
	s_and_saveexec_b64 s[0:1], vcc
	s_xor_b64 s[0:1], exec, s[0:1]
	s_cbranch_execz .LBB0_193
	v_subrev_u32_e32 v0, 20, v2
	v_cvt_f32_u32_e32 v0, v0
	s_movk_i32 s5, 0xee00
	s_mov_b32 s9, 0xc2fc0000
	v_mad_u64_u32 v[2:3], s[12:13], v43, s5, v[38:39]
	v_sub_f32_e32 v0, 0xc0a00000, v0
	v_cmp_gt_f32_e32 vcc, s9, v0
	s_mov_b32 s5, 0x800000
	v_readlane_b32 s20, v252, 10
	v_cndmask_b32_e32 v3, 0, v250, vcc
	v_add_f32_e32 v0, v0, v3
	v_exp_f32_e32 v0, v0
	v_cndmask_b32_e32 v3, 0, v162, vcc
	v_readlane_b32 s21, v252, 11
	v_mov_b32_e32 v51, 0x60
	v_ldexp_f32 v0, v0, v3
	v_sub_f32_e32 v5, 1.0, v0
	v_mov_b32_e32 v3, v1
	v_lshl_add_u64 v[2:3], v[2:3], 1, v[6:7]
	v_lshlrev_b32_e32 v0, 1, v32
	v_cmp_gt_f32_e32 vcc, s5, v5
	v_lshl_add_u64 v[82:83], v[2:3], 0, v[0:1]
	v_mov_b32_e32 v2, 0x42000000
	v_cndmask_b32_e64 v0, 0, 32, vcc
	v_ldexp_f32 v0, v5, v0
	v_log_f32_e32 v0, v0
	v_cndmask_b32_e32 v2, 0, v2, vcc
	v_mov_b32_e32 v5, v1
	s_movk_i32 s5, 0x7f
	v_sub_f32_e32 v0, v0, v2
	global_load_ushort v2, v[82:83], off offset:3632
	global_load_ushort v3, v[82:83], off offset:3760
	global_load_dwordx2 v[6:7], v4, s[20:21]
	v_lshl_add_u64 v[16:17], s[20:21], 0, v[4:5]
	v_readlane_b32 s12, v252, 26
	v_readlane_b32 s13, v252, 27
	s_waitcnt vmcnt(2)
	v_lshlrev_b32_e32 v2, 16, v2
	s_waitcnt vmcnt(1)
	v_lshlrev_b32_e32 v3, 16, v3
	s_waitcnt vmcnt(0)
	v_pk_mul_f32 v[8:9], v[6:7], v[2:3]
	v_pk_mul_f32 v[2:3], v[6:7], v[2:3] op_sel:[0,1] op_sel_hi:[1,0]
	v_sub_f32_e32 v52, v8, v9
	v_add_f32_e32 v5, v2, v3
	v_bitop3_b32 v2, v45, s5, v51 bitop3:0x6c
	v_cvt_f32_ubyte0_e32 v2, v2
	v_mul_f32_e32 v3, v0, v2
	v_cmp_gt_f32_e32 vcc, s9, v3
	s_movk_i32 s5, 0x7e
	v_mul_f32_e32 v90, 0x3db504f3, v52
	v_cndmask_b32_e32 v3, 0, v250, vcc
	v_fmac_f32_e32 v3, v0, v2
	v_exp_f32_e32 v2, v3
	v_cndmask_b32_e32 v3, 0, v162, vcc
	v_mul_f32_e32 v190, 0x3db504f3, v5
	v_cvt_pk_bf16_f32 v174, v90, s0
	v_ldexp_f32 v26, v2, v3
	v_bitop3_b32 v2, v45, s5, v51 bitop3:0x6c
	v_cvt_f32_ubyte0_e32 v2, v2
	v_mul_f32_e32 v3, v0, v2
	v_cmp_gt_f32_e32 vcc, s9, v3
	s_movk_i32 s5, 0x7d
	v_cvt_pk_bf16_f32 v5, v190, s0
	v_cndmask_b32_e32 v3, 0, v250, vcc
	v_fmac_f32_e32 v3, v0, v2
	v_exp_f32_e32 v2, v3
	v_cndmask_b32_e32 v3, 0, v162, vcc
	v_ldexp_f32 v2, v2, v3
	v_bitop3_b32 v3, v45, s5, v51 bitop3:0x6c
	v_cvt_f32_ubyte0_e32 v3, v3
	v_mul_f32_e32 v6, v0, v3
	v_cmp_gt_f32_e32 vcc, s9, v6
	s_movk_i32 s5, 0x7c
	s_nop 0
	v_cndmask_b32_e32 v6, 0, v250, vcc
	v_fmac_f32_e32 v6, v0, v3
	v_exp_f32_e32 v3, v6
	v_cndmask_b32_e32 v6, 0, v162, vcc
	v_ldexp_f32 v27, v3, v6
	v_bitop3_b32 v3, v45, s5, v51 bitop3:0x6c
	v_cvt_f32_ubyte0_e32 v3, v3
	v_mul_f32_e32 v6, v0, v3
	v_cmp_gt_f32_e32 vcc, s9, v6
	s_movk_i32 s5, 0x7b
	s_nop 0
	v_cndmask_b32_e32 v6, 0, v250, vcc
	v_fmac_f32_e32 v6, v0, v3
	v_exp_f32_e32 v3, v6
	v_cndmask_b32_e32 v6, 0, v162, vcc
	v_ldexp_f32 v3, v3, v6
	v_bitop3_b32 v6, v45, s5, v51 bitop3:0x6c
	v_cvt_f32_ubyte0_e32 v6, v6
	v_mul_f32_e32 v7, v0, v6
	v_cmp_gt_f32_e32 vcc, s9, v7
	s_movk_i32 s5, 0x7a
	s_nop 0
	v_cndmask_b32_e32 v7, 0, v250, vcc
	v_fmac_f32_e32 v7, v0, v6
	v_exp_f32_e32 v6, v7
	v_cndmask_b32_e32 v7, 0, v162, vcc
	v_ldexp_f32 v68, v6, v7
	v_bitop3_b32 v6, v45, s5, v51 bitop3:0x6c
	v_cvt_f32_ubyte0_e32 v6, v6
	v_mul_f32_e32 v7, v0, v6
	v_cmp_gt_f32_e32 vcc, s9, v7
	s_movk_i32 s5, 0x79
	s_nop 0
	v_cndmask_b32_e32 v7, 0, v250, vcc
	v_fmac_f32_e32 v7, v0, v6
	v_exp_f32_e32 v6, v7
	v_cndmask_b32_e32 v7, 0, v162, vcc
	v_ldexp_f32 v28, v6, v7
	v_bitop3_b32 v6, v45, s5, v51 bitop3:0x6c
	v_cvt_f32_ubyte0_e32 v6, v6
	v_mul_f32_e32 v7, v0, v6
	v_cmp_gt_f32_e32 vcc, s9, v7
	s_movk_i32 s5, 0x78
	s_nop 0
	v_cndmask_b32_e32 v7, 0, v250, vcc
	v_fmac_f32_e32 v7, v0, v6
	v_exp_f32_e32 v6, v7
	v_cndmask_b32_e32 v7, 0, v162, vcc
	v_ldexp_f32 v69, v6, v7
	v_bitop3_b32 v6, v45, s5, v51 bitop3:0x6c
	v_cvt_f32_ubyte0_e32 v6, v6
	v_mul_f32_e32 v7, v0, v6
	v_cmp_gt_f32_e32 vcc, s9, v7
	s_movk_i32 s5, 0x77
	s_nop 0
	v_cndmask_b32_e32 v7, 0, v250, vcc
	v_fmac_f32_e32 v7, v0, v6
	v_exp_f32_e32 v6, v7
	v_cndmask_b32_e32 v7, 0, v162, vcc
	v_ldexp_f32 v29, v6, v7
	v_bitop3_b32 v6, v45, s5, v51 bitop3:0x6c
	v_cvt_f32_ubyte0_e32 v6, v6
	v_mul_f32_e32 v7, v0, v6
	v_cmp_gt_f32_e32 vcc, s9, v7
	s_movk_i32 s5, 0x76
	s_nop 0
	v_cndmask_b32_e32 v7, 0, v250, vcc
	v_fmac_f32_e32 v7, v0, v6
	v_exp_f32_e32 v6, v7
	v_cndmask_b32_e32 v7, 0, v162, vcc
	v_ldexp_f32 v10, v6, v7
	v_bitop3_b32 v6, v45, s5, v51 bitop3:0x6c
	v_cvt_f32_ubyte0_e32 v6, v6
	v_mul_f32_e32 v7, v0, v6
	v_cmp_gt_f32_e32 vcc, s9, v7
	s_movk_i32 s5, 0x75
	s_nop 0
	v_cndmask_b32_e32 v7, 0, v250, vcc
	v_fmac_f32_e32 v7, v0, v6
	v_exp_f32_e32 v6, v7
	v_cndmask_b32_e32 v7, 0, v162, vcc
	v_ldexp_f32 v6, v6, v7
	v_bitop3_b32 v7, v45, s5, v51 bitop3:0x6c
	v_cvt_f32_ubyte0_e32 v7, v7
	v_mul_f32_e32 v8, v0, v7
; DI bf16_t f2bf(float a) { return (bf16_t)(pack2(a, 0.f) & 0xffffu); }
; DI void post_z(const Params& p, int layer) {
;     ...
;         float zeta = exp2f(lg2 * (float)(127 - ((spos + i) & 127)));
;         u1[i] = f2bf(o1 * zeta);
;         u2[i] = f2bf(o2 * zeta);
	v_cmp_gt_f32_e32 vcc, s9, v8
	s_movk_i32 s5, 0x74
	s_nop 0
	v_cndmask_b32_e32 v8, 0, v250, vcc
	v_fmac_f32_e32 v8, v0, v7
	v_exp_f32_e32 v7, v8
	v_cndmask_b32_e32 v8, 0, v162, vcc
	v_ldexp_f32 v11, v7, v8
	v_bitop3_b32 v7, v45, s5, v51 bitop3:0x6c
	v_cvt_f32_ubyte0_e32 v7, v7
	v_mul_f32_e32 v8, v0, v7
	v_cmp_gt_f32_e32 vcc, s9, v8
	s_movk_i32 s5, 0x73
	s_nop 0
	v_cndmask_b32_e32 v8, 0, v250, vcc
	v_fmac_f32_e32 v8, v0, v7
	v_exp_f32_e32 v7, v8
	v_cndmask_b32_e32 v8, 0, v162, vcc
	v_ldexp_f32 v7, v7, v8
	v_bitop3_b32 v8, v45, s5, v51 bitop3:0x6c
	v_cvt_f32_ubyte0_e32 v8, v8
	v_mul_f32_e32 v9, v0, v8
	v_cmp_gt_f32_e32 vcc, s9, v9
	s_movk_i32 s5, 0x72
	s_nop 0
	v_cndmask_b32_e32 v9, 0, v250, vcc
	v_fmac_f32_e32 v9, v0, v8
	v_exp_f32_e32 v8, v9
	v_cndmask_b32_e32 v9, 0, v162, vcc
	v_ldexp_f32 v12, v8, v9
	v_bitop3_b32 v8, v45, s5, v51 bitop3:0x6c
	v_cvt_f32_ubyte0_e32 v8, v8
	v_mul_f32_e32 v9, v0, v8
	v_cmp_gt_f32_e32 vcc, s9, v9
	s_movk_i32 s5, 0x71
	s_nop 0
	v_cndmask_b32_e32 v9, 0, v250, vcc
	v_fmac_f32_e32 v9, v0, v8
	v_exp_f32_e32 v8, v9
	v_cndmask_b32_e32 v9, 0, v162, vcc
	v_ldexp_f32 v8, v8, v9
	v_bitop3_b32 v9, v45, s5, v51 bitop3:0x6c
	v_cvt_f32_ubyte0_e32 v9, v9
	v_mul_f32_e32 v13, v0, v9
	v_cmp_gt_f32_e32 vcc, s9, v13
	s_movk_i32 s5, 0x70
	s_nop 0
	v_cndmask_b32_e32 v13, 0, v250, vcc
	v_fmac_f32_e32 v13, v0, v9
	v_exp_f32_e32 v9, v13
	v_cndmask_b32_e32 v13, 0, v162, vcc
	v_ldexp_f32 v13, v9, v13
	v_bitop3_b32 v9, v45, s5, v51 bitop3:0x6c
	v_cvt_f32_ubyte0_e32 v9, v9
	v_mul_f32_e32 v14, v0, v9
	v_cmp_gt_f32_e32 vcc, s9, v14
	s_movk_i32 s5, 0x6f
	s_nop 0
	v_cndmask_b32_e32 v14, 0, v250, vcc
	v_fmac_f32_e32 v14, v0, v9
	v_exp_f32_e32 v9, v14
	v_cndmask_b32_e32 v14, 0, v162, vcc
	v_ldexp_f32 v9, v9, v14
	v_bitop3_b32 v14, v45, s5, v51 bitop3:0x6c
	v_cvt_f32_ubyte0_e32 v14, v14
	v_mul_f32_e32 v15, v0, v14
	v_cmp_gt_f32_e32 vcc, s9, v15
	s_movk_i32 s5, 0x6e
	s_nop 0
	v_cndmask_b32_e32 v15, 0, v250, vcc
	v_fmac_f32_e32 v15, v0, v14
	v_exp_f32_e32 v14, v15
	v_cndmask_b32_e32 v15, 0, v162, vcc
	v_ldexp_f32 v18, v14, v15
	v_bitop3_b32 v14, v45, s5, v51 bitop3:0x6c
	v_cvt_f32_ubyte0_e32 v14, v14
	v_mul_f32_e32 v15, v0, v14
	v_cmp_gt_f32_e32 vcc, s9, v15
	s_movk_i32 s5, 0x6d
	s_nop 0
	v_cndmask_b32_e32 v15, 0, v250, vcc
	v_fmac_f32_e32 v15, v0, v14
	v_exp_f32_e32 v14, v15
	v_cndmask_b32_e32 v15, 0, v162, vcc
	v_ldexp_f32 v14, v14, v15
	v_bitop3_b32 v15, v45, s5, v51 bitop3:0x6c
	v_cvt_f32_ubyte0_e32 v15, v15
	v_mul_f32_e32 v19, v0, v15
	v_cmp_gt_f32_e32 vcc, s9, v19
	s_movk_i32 s5, 0x6c
	s_nop 0
	v_cndmask_b32_e32 v19, 0, v250, vcc
	v_fmac_f32_e32 v19, v0, v15
	v_exp_f32_e32 v15, v19
	v_cndmask_b32_e32 v19, 0, v162, vcc
	v_ldexp_f32 v19, v15, v19
	v_bitop3_b32 v15, v45, s5, v51 bitop3:0x6c
	v_cvt_f32_ubyte0_e32 v15, v15
	v_mul_f32_e32 v20, v0, v15
	v_cmp_gt_f32_e32 vcc, s9, v20
	s_movk_i32 s5, 0x6b
	s_nop 0
	v_cndmask_b32_e32 v20, 0, v250, vcc
	v_fmac_f32_e32 v20, v0, v15
	v_exp_f32_e32 v15, v20
	v_cndmask_b32_e32 v20, 0, v162, vcc
	v_ldexp_f32 v15, v15, v20
	v_bitop3_b32 v20, v45, s5, v51 bitop3:0x6c
	v_cvt_f32_ubyte0_e32 v20, v20
	v_mul_f32_e32 v21, v0, v20
	v_cmp_gt_f32_e32 vcc, s9, v21
	s_movk_i32 s5, 0x6a
	s_nop 0
	v_cndmask_b32_e32 v21, 0, v250, vcc
	v_fmac_f32_e32 v21, v0, v20
	v_exp_f32_e32 v20, v21
	v_cndmask_b32_e32 v21, 0, v162, vcc
	v_ldexp_f32 v48, v20, v21
	v_bitop3_b32 v20, v45, s5, v51 bitop3:0x6c
	v_cvt_f32_ubyte0_e32 v20, v20
	v_mul_f32_e32 v21, v0, v20
	v_cmp_gt_f32_e32 vcc, s9, v21
	s_movk_i32 s5, 0x69
	s_nop 0
	v_cndmask_b32_e32 v21, 0, v250, vcc
	v_fmac_f32_e32 v21, v0, v20
	v_exp_f32_e32 v20, v21
	v_cndmask_b32_e32 v21, 0, v162, vcc
	v_ldexp_f32 v20, v20, v21
	v_bitop3_b32 v21, v45, s5, v51 bitop3:0x6c
	v_cvt_f32_ubyte0_e32 v21, v21
	v_mul_f32_e32 v22, v0, v21
	v_cmp_gt_f32_e32 vcc, s9, v22
	s_movk_i32 s5, 0x68
	s_nop 0
	v_cndmask_b32_e32 v22, 0, v250, vcc
	v_fmac_f32_e32 v22, v0, v21
	v_exp_f32_e32 v21, v22
	v_cndmask_b32_e32 v22, 0, v162, vcc
	v_ldexp_f32 v49, v21, v22
	v_bitop3_b32 v21, v45, s5, v51 bitop3:0x6c
	v_cvt_f32_ubyte0_e32 v21, v21
	v_mul_f32_e32 v22, v0, v21
	v_cmp_gt_f32_e32 vcc, s9, v22
	s_movk_i32 s5, 0x67
	s_nop 0
	v_cndmask_b32_e32 v22, 0, v250, vcc
	v_fmac_f32_e32 v22, v0, v21
	v_exp_f32_e32 v21, v22
	v_cndmask_b32_e32 v22, 0, v162, vcc
	v_ldexp_f32 v21, v21, v22
	v_bitop3_b32 v22, v45, s5, v51 bitop3:0x6c
	v_cvt_f32_ubyte0_e32 v22, v22
	v_mul_f32_e32 v23, v0, v22
	v_cmp_gt_f32_e32 vcc, s9, v23
	s_movk_i32 s5, 0x66
	s_nop 0
	v_cndmask_b32_e32 v23, 0, v250, vcc
	v_fmac_f32_e32 v23, v0, v22
	v_exp_f32_e32 v22, v23
	v_cndmask_b32_e32 v23, 0, v162, vcc
	v_ldexp_f32 v24, v22, v23
	v_bitop3_b32 v22, v45, s5, v51 bitop3:0x6c
	v_cvt_f32_ubyte0_e32 v22, v22
	v_mul_f32_e32 v23, v0, v22
	v_cmp_gt_f32_e32 vcc, s9, v23
	s_movk_i32 s5, 0x65
	s_nop 0
	v_cndmask_b32_e32 v23, 0, v250, vcc
	v_fmac_f32_e32 v23, v0, v22
	v_exp_f32_e32 v22, v23
	v_cndmask_b32_e32 v23, 0, v162, vcc
	v_ldexp_f32 v22, v22, v23
	v_bitop3_b32 v23, v45, s5, v51 bitop3:0x6c
	v_cvt_f32_ubyte0_e32 v23, v23
	v_mul_f32_e32 v25, v0, v23
	v_cmp_gt_f32_e32 vcc, s9, v25
	s_movk_i32 s5, 0x64
	s_nop 0
	v_cndmask_b32_e32 v25, 0, v250, vcc
	v_fmac_f32_e32 v25, v0, v23
	v_exp_f32_e32 v23, v25
	v_cndmask_b32_e32 v25, 0, v162, vcc
	v_ldexp_f32 v25, v23, v25
	v_bitop3_b32 v23, v45, s5, v51 bitop3:0x6c
	v_cvt_f32_ubyte0_e32 v23, v23
	v_mul_f32_e32 v44, v0, v23
	v_cmp_gt_f32_e32 vcc, s9, v44
	s_movk_i32 s5, 0x63
	s_nop 0
	v_cndmask_b32_e32 v44, 0, v250, vcc
	v_fmac_f32_e32 v44, v0, v23
	v_exp_f32_e32 v23, v44
	v_cndmask_b32_e32 v44, 0, v162, vcc
	v_ldexp_f32 v23, v23, v44
	v_bitop3_b32 v44, v45, s5, v51 bitop3:0x6c
	v_cvt_f32_ubyte0_e32 v44, v44
; DI bf16_t f2bf(float a) { return (bf16_t)(pack2(a, 0.f) & 0xffffu); }
; DI float bf2f(bf16_t h) { return __uint_as_float(((unsigned)h) << 16); }
; DI void post_z(const Params& p, int layer) {
;     ...
; #pragma unroll
;       for (int i = 0; i < 32; ++i) {
;         const bf16_t* p1 = zr + (size_t)i * ZS + colbase + lane;
;         x1[i] = bf2f(p1[0]);
;         x2[i] = bf2f(p1[64]);
;       }
;       unsigned u1[32], u2[32];
; #pragma unroll
;       for (int i = 0; i < 32; ++i) {
;         bf16_t* p1 = zr + (size_t)i * ZS + colbase + lane;
;         float2 cs = rope[(spos + i) * 64 + lane];
;         float o1 = (x1[i] * cs.x - x2[i] * cs.y) * 0.08838834764831845f;
;         float o2 = (x1[i] * cs.y + x2[i] * cs.x) * 0.08838834764831845f;
;         p1[0] = f2bf(o1);
;         p1[64] = f2bf(o2);
;         float zeta = exp2f(lg2 * (float)(127 - ((spos + i) & 127)));
;         u1[i] = f2bf(o1 * zeta);
;         u2[i] = f2bf(o2 * zeta);
;       }
;       bf16_t* d1 = kzT + ((size_t)((b * 4 + h) * 128 + lane)) * TS + spos;
	v_mul_f32_e32 v46, v0, v44
	v_cmp_gt_f32_e32 vcc, s9, v46
	s_movk_i32 s5, 0x62
	s_nop 0
	v_cndmask_b32_e32 v46, 0, v250, vcc
	v_fmac_f32_e32 v46, v0, v44
	v_exp_f32_e32 v44, v46
	v_cndmask_b32_e32 v46, 0, v162, vcc
	v_ldexp_f32 v46, v44, v46
	v_bitop3_b32 v44, v45, s5, v51 bitop3:0x6c
	v_cvt_f32_ubyte0_e32 v44, v44
	v_mul_f32_e32 v47, v0, v44
	v_cmp_gt_f32_e32 vcc, s9, v47
	s_movk_i32 s5, 0x61
	s_nop 0
	v_cndmask_b32_e32 v47, 0, v250, vcc
	v_fmac_f32_e32 v47, v0, v44
	v_exp_f32_e32 v44, v47
	v_cndmask_b32_e32 v47, 0, v162, vcc
	v_ldexp_f32 v44, v44, v47
	v_bitop3_b32 v47, v45, s5, v51 bitop3:0x6c
	v_cvt_f32_ubyte0_e32 v47, v47
	v_mul_f32_e32 v51, v0, v47
	v_cmp_gt_f32_e32 vcc, s9, v51
	s_movk_i32 s5, 0x60
	v_bitop3_b32 v45, v45, s5, v45 bitop3:0xc
	v_cndmask_b32_e32 v51, 0, v250, vcc
	v_fmac_f32_e32 v51, v0, v47
	v_exp_f32_e32 v47, v51
	v_cndmask_b32_e32 v51, 0, v162, vcc
	v_cvt_f32_ubyte0_e32 v45, v45
	s_movk_i32 s5, 0x1200
	v_ldexp_f32 v47, v47, v51
	v_mul_f32_e32 v51, v0, v45
	v_cmp_gt_f32_e32 vcc, s9, v51
	v_mul_lo_u32 v43, v43, s5
	s_movk_i32 s5, 0x4080
	v_cndmask_b32_e32 v51, 0, v250, vcc
	v_fmac_f32_e32 v51, v0, v45
	v_exp_f32_e32 v0, v51
	v_cndmask_b32_e32 v45, 0, v162, vcc
	s_mov_b32 s9, 0x800000
	v_ldexp_f32 v45, v0, v45
	v_lshlrev_b32_e32 v0, 9, v50
	v_sub_u32_e32 v0, v0, v43
	v_add3_u32 v0, v32, v38, v0
	v_mov_b64_e32 v[50:51], s[12:13]
	v_mad_i64_i32 v[50:51], s[12:13], v0, s5, v[50:51]
	s_movk_i32 s12, 0x3000
	s_nop 0
	v_add_co_u32_e32 v94, vcc, s12, v82
	s_movk_i32 s5, 0x6000
	s_nop 0
	v_addc_co_u32_e32 v95, vcc, 0, v83, vcc
	v_add_co_u32_e32 v122, vcc, s5, v82
	s_mov_b32 s5, 0x8000
	s_nop 0
	v_addc_co_u32_e32 v123, vcc, 0, v83, vcc
	v_add_co_u32_e32 v120, vcc, s5, v82
	s_mov_b32 s5, 0xb000
	s_nop 0
	v_addc_co_u32_e32 v121, vcc, 0, v83, vcc
	v_add_co_u32_e32 v118, vcc, s5, v82
	s_mov_b32 s5, 0xe000
	s_nop 0
	v_addc_co_u32_e32 v119, vcc, 0, v83, vcc
	v_add_co_u32_e32 v116, vcc, s5, v82
	s_mov_b32 s5, 0x10000
	s_nop 0
	v_addc_co_u32_e32 v117, vcc, 0, v83, vcc
	v_add_co_u32_e32 v114, vcc, s5, v82
	s_mov_b32 s5, 0x13000
	s_nop 0
	v_addc_co_u32_e32 v115, vcc, 0, v83, vcc
	v_add_co_u32_e32 v112, vcc, s5, v82
	s_mov_b32 s5, 0x15000
	s_nop 0
	v_addc_co_u32_e32 v113, vcc, 0, v83, vcc
	v_add_co_u32_e32 v110, vcc, s5, v82
	s_mov_b32 s5, 0x16000
	s_nop 0
	v_addc_co_u32_e32 v111, vcc, 0, v83, vcc
	v_add_co_u32_e32 v108, vcc, s5, v82
	s_mov_b32 s5, 0x18000
	s_nop 0
	v_addc_co_u32_e32 v109, vcc, 0, v83, vcc
	v_add_co_u32_e32 v106, vcc, s5, v82
	s_mov_b32 s5, 0x1b000
	s_nop 0
	v_addc_co_u32_e32 v107, vcc, 0, v83, vcc
	v_add_co_u32_e32 v104, vcc, s5, v82
	s_mov_b32 s5, 0x1d000
	s_nop 0
	v_addc_co_u32_e32 v105, vcc, 0, v83, vcc
	v_add_co_u32_e32 v102, vcc, s5, v82
	s_mov_b32 s5, 0x20000
	s_nop 0
	v_addc_co_u32_e32 v103, vcc, 0, v83, vcc
	v_add_co_u32_e32 v100, vcc, s5, v82
	s_mov_b32 s5, 0x23000
	s_nop 0
	v_addc_co_u32_e32 v101, vcc, 0, v83, vcc
	v_add_co_u32_e32 v98, vcc, s5, v82
	s_mov_b32 s5, 0x25000
	s_nop 0
	v_addc_co_u32_e32 v99, vcc, 0, v83, vcc
	v_add_co_u32_e32 v96, vcc, s5, v82
	s_mov_b32 s5, 0x28000
	s_nop 0
	v_addc_co_u32_e32 v97, vcc, 0, v83, vcc
	v_add_co_u32_e32 v92, vcc, s5, v82
	s_mov_b32 s5, 0x2b000
	s_nop 0
	v_addc_co_u32_e32 v93, vcc, 0, v83, vcc
	v_add_co_u32_e32 v88, vcc, s5, v82
	s_mov_b32 s5, 0x2d000
	s_nop 0
	v_addc_co_u32_e32 v89, vcc, 0, v83, vcc
	v_add_co_u32_e32 v86, vcc, s5, v82
	s_mov_b32 s5, 0x30000
	s_nop 0
	v_addc_co_u32_e32 v87, vcc, 0, v83, vcc
	v_add_co_u32_e32 v84, vcc, s5, v82
	s_mov_b32 s5, 0x33000
	s_nop 0
	v_addc_co_u32_e32 v85, vcc, 0, v83, vcc
	v_add_co_u32_e32 v78, vcc, s5, v82
	s_mov_b32 s5, 0x32000
	s_nop 0
	v_addc_co_u32_e32 v79, vcc, 0, v83, vcc
	v_add_co_u32_e32 v80, vcc, s5, v82
	s_mov_b32 s5, 0x35000
	s_nop 0
	v_addc_co_u32_e32 v81, vcc, 0, v83, vcc
	v_add_co_u32_e32 v76, vcc, s5, v82
	s_mov_b32 s5, 0x38000
	s_nop 0
	v_addc_co_u32_e32 v77, vcc, 0, v83, vcc
	v_add_co_u32_e32 v74, vcc, s5, v82
	s_mov_b32 s5, 0x3a000
	s_nop 0
	v_addc_co_u32_e32 v75, vcc, 0, v83, vcc
	v_add_co_u32_e32 v72, vcc, s5, v82
	s_mov_b32 s5, 0x3d000
	s_nop 0
	v_addc_co_u32_e32 v73, vcc, 0, v83, vcc
	v_add_co_u32_e32 v70, vcc, s5, v82
	s_mov_b32 s5, 0x40000
	s_nop 0
	v_addc_co_u32_e32 v71, vcc, 0, v83, vcc
	v_add_co_u32_e32 v66, vcc, s5, v82
	s_mov_b32 s5, 0x42000
	s_nop 0
	v_addc_co_u32_e32 v67, vcc, 0, v83, vcc
	v_add_co_u32_e32 v64, vcc, s5, v82
	s_mov_b32 s5, 0x45000
	s_nop 0
	v_addc_co_u32_e32 v65, vcc, 0, v83, vcc
	v_add_co_u32_e32 v62, vcc, s5, v82
	s_mov_b32 s5, 0x48000
	s_nop 0
	v_addc_co_u32_e32 v63, vcc, 0, v83, vcc
	v_add_co_u32_e32 v60, vcc, s5, v82
	s_mov_b32 s5, 0x4a000
	s_nop 0
	v_addc_co_u32_e32 v61, vcc, 0, v83, vcc
	v_add_co_u32_e32 v58, vcc, s5, v82
	s_mov_b32 s5, 0x4d000
	s_nop 0
	v_addc_co_u32_e32 v59, vcc, 0, v83, vcc
	v_add_co_u32_e32 v56, vcc, s5, v82
	s_mov_b32 s5, 0x50000
	s_nop 0
	v_addc_co_u32_e32 v57, vcc, 0, v83, vcc
	v_add_co_u32_e32 v52, vcc, s5, v82
	s_mov_b32 s5, 0x4f000
	s_nop 0
	v_addc_co_u32_e32 v53, vcc, 0, v83, vcc
	v_add_co_u32_e32 v54, vcc, s5, v82
	v_lshlrev_b32_e32 v0, 1, v42
	s_nop 0
	v_addc_co_u32_e32 v55, vcc, 0, v83, vcc
	s_mov_b32 s5, 0x52000
	v_lshl_add_u64 v[42:43], v[50:51], 0, v[0:1]
	v_add_co_u32_e32 v50, vcc, s5, v82
	global_load_ushort v91, v[94:95], off offset:2272
	global_load_ushort v158, v[94:95], off offset:2144
	v_addc_co_u32_e32 v51, vcc, 0, v83, vcc
	global_load_ushort v187, v[122:123], off offset:784
	global_load_ushort v188, v[122:123], off offset:656
	global_load_ushort v185, v[120:121], off offset:3392
	global_load_ushort v186, v[120:121], off offset:3264
	global_load_ushort v183, v[118:119], off offset:1776
	global_load_ushort v184, v[118:119], off offset:1904
; DI bf16_t f2bf(float a) { return (bf16_t)(pack2(a, 0.f) & 0xffffu); }
; DI float bf2f(bf16_t h) { return __uint_as_float(((unsigned)h) << 16); }
; DI void post_z(const Params& p, int layer) {
;     ...
; #pragma unroll
;       for (int i = 0; i < 32; ++i) {
;         const bf16_t* p1 = zr + (size_t)i * ZS + colbase + lane;
;         x1[i] = bf2f(p1[0]);
;         x2[i] = bf2f(p1[64]);
;       }
;       unsigned u1[32], u2[32];
; #pragma unroll
;       for (int i = 0; i < 32; ++i) {
;         bf16_t* p1 = zr + (size_t)i * ZS + colbase + lane;
;         float2 cs = rope[(spos + i) * 64 + lane];
;         float o1 = (x1[i] * cs.x - x2[i] * cs.y) * 0.08838834764831845f;
;         float o2 = (x1[i] * cs.y + x2[i] * cs.x) * 0.08838834764831845f;
;         p1[0] = f2bf(o1);
;         p1[64] = f2bf(o2);
;         float zeta = exp2f(lg2 * (float)(127 - ((spos + i) & 127)));
;         u1[i] = f2bf(o1 * zeta);
;         u2[i] = f2bf(o2 * zeta);
;       }
	global_load_ushort v181, v[116:117], off offset:416
	global_load_ushort v182, v[116:117], off offset:288
	global_load_ushort v179, v[114:115], off offset:3024
	global_load_ushort v180, v[114:115], off offset:2896
	global_load_ushort v177, v[112:113], off offset:1536
	global_load_ushort v178, v[112:113], off offset:1408
	global_load_ushort v175, v[110:111], off offset:4016
	global_load_ushort v176, v[108:109], off offset:48
	global_load_ushort v172, v[106:107], off offset:2656
	global_load_ushort v173, v[106:107], off offset:2528
	global_load_ushort v170, v[104:105], off offset:1168
	global_load_ushort v171, v[104:105], off offset:1040
	global_load_ushort v168, v[102:103], off offset:3776
	global_load_ushort v169, v[102:103], off offset:3648
	global_load_ushort v166, v[100:101], off offset:2160
	global_load_ushort v167, v[100:101], off offset:2288
	global_load_ushort v164, v[98:99], off offset:800
	global_load_ushort v165, v[98:99], off offset:672
	global_load_ushort v161, v[96:97], off offset:3408
	global_load_ushort v163, v[96:97], off offset:3280
	global_load_ushort v159, v[92:93], off offset:1920
	global_load_ushort v160, v[92:93], off offset:1792
	global_load_ushort v156, v[88:89], off offset:304
	global_load_ushort v157, v[88:89], off offset:432
	global_load_ushort v154, v[86:87], off offset:3040
	global_load_ushort v155, v[86:87], off offset:2912
	global_load_ushort v152, v[84:85], off offset:1552
	global_load_ushort v153, v[84:85], off offset:1424
	global_load_ushort v150, v[78:79], off offset:64
	global_load_ushort v151, v[80:81], off offset:4032
	global_load_ushort v148, v[76:77], off offset:2544
	global_load_ushort v149, v[76:77], off offset:2672
	global_load_ushort v146, v[74:75], off offset:1184
	global_load_ushort v147, v[74:75], off offset:1056
	global_load_ushort v144, v[72:73], off offset:3792
	global_load_ushort v145, v[72:73], off offset:3664
	global_load_ushort v142, v[70:71], off offset:2304
	global_load_ushort v143, v[70:71], off offset:2176
	global_load_ushort v140, v[66:67], off offset:688
	global_load_ushort v141, v[66:67], off offset:816
	global_load_ushort v138, v[64:65], off offset:3424
	global_load_ushort v139, v[64:65], off offset:3296
	global_load_ushort v136, v[62:63], off offset:1936
	global_load_ushort v137, v[62:63], off offset:1808
	global_load_ushort v134, v[60:61], off offset:448
	global_load_ushort v135, v[60:61], off offset:320
	global_load_ushort v132, v[58:59], off offset:2928
	global_load_ushort v133, v[58:59], off offset:3056
	global_load_ushort v130, v[56:57], off offset:1568
	global_load_ushort v131, v[56:57], off offset:1440
	global_load_ushort v128, v[52:53], off offset:80
	global_load_ushort v129, v[54:55], off offset:4048
	global_load_ushort v0, v[50:51], off offset:2688
	global_load_ushort v127, v[50:51], off offset:2560
	s_movk_i32 s5, 0x1000
	global_store_short v[82:83], v174, off offset:3632
	global_store_short v[82:83], v5, off offset:3760
	v_mov_b32_e32 v212, v4
	s_add_u32 s48, s20, 0x1000
	s_addc_u32 s49, s21, 0
	s_add_u32 s50, s20, 0x2000
	s_addc_u32 s51, s21, 0
	s_add_u32 s52, s20, 0x3000
	s_addc_u32 s53, s21, 0
	global_load_dwordx2 v[198:199], v4, s[20:21] offset:512
	global_load_dwordx2 v[200:201], v4, s[20:21] offset:1024
	global_load_dwordx2 v[202:203], v4, s[20:21] offset:1536
	global_load_dwordx2 v[204:205], v4, s[20:21] offset:2048
	global_load_dwordx2 v[206:207], v4, s[20:21] offset:2560
	global_load_dwordx2 v[208:209], v4, s[20:21] offset:3072
	global_load_dwordx2 v[210:211], v4, s[20:21] offset:3584
	global_load_dwordx2 v[216:217], v4, s[48:49]
	global_load_dwordx2 v[218:219], v4, s[48:49] offset:512
	global_load_dwordx2 v[220:221], v4, s[48:49] offset:1024
	global_load_dwordx2 v[222:223], v4, s[48:49] offset:1536
	global_load_dwordx2 v[224:225], v4, s[48:49] offset:2048
	global_load_dwordx2 v[226:227], v4, s[48:49] offset:2560
	global_load_dwordx2 v[228:229], v4, s[48:49] offset:3072
	global_load_dwordx2 v[230:231], v4, s[48:49] offset:3584
	global_load_dwordx2 v[232:233], v4, s[50:51]
	global_load_dwordx2 v[234:235], v4, s[50:51] offset:512
	global_load_dwordx2 v[236:237], v4, s[50:51] offset:1024
	global_load_dwordx2 v[238:239], v4, s[50:51] offset:1536
	global_load_dwordx2 v[240:241], v4, s[50:51] offset:2048
	global_load_dwordx2 v[242:243], v4, s[50:51] offset:2560
	global_load_dwordx2 v[244:245], v4, s[50:51] offset:3072
	global_load_dwordx2 v[246:247], v4, s[50:51] offset:3584
	global_load_dwordx2 v[248:249], v4, s[52:53]
	s_nop 0
	s_nop 0
	s_waitcnt vmcnt(63)
	v_lshlrev_b32_e32 v82, 16, v91
	s_waitcnt vmcnt(63)
	v_lshlrev_b32_e32 v83, 16, v158
	s_nop 0
	s_waitcnt vmcnt(23)
	v_pk_mul_f32 v[194:195], v[198:199], v[82:83] op_sel:[0,1] op_sel_hi:[1,0]
	s_nop 0
	v_sub_f32_e32 v5, v194, v195
	v_pk_mul_f32 v[82:83], v[198:199], v[82:83]
	global_load_dwordx2 v[198:199], v212, s[52:53] offset:512
	v_mul_f32_e32 v194, 0x3db504f3, v5
	v_add_f32_e32 v5, v82, v83
	v_mul_f32_e32 v82, 0x3db504f3, v5
	v_cvt_pk_bf16_f32 v5, v194, s0
	global_store_short v[94:95], v5, off offset:2144
	v_cvt_pk_bf16_f32 v5, v82, s0
	global_store_short v[94:95], v5, off offset:2272
	v_lshlrev_b32_e32 v95, 16, v188
	s_nop 0
	v_lshlrev_b32_e32 v94, 16, v187
	s_nop 0
	s_waitcnt vmcnt(25)
	v_pk_mul_f32 v[192:193], v[200:201], v[94:95] op_sel:[0,1] op_sel_hi:[1,0]
	s_nop 0
	v_sub_f32_e32 v5, v192, v193
	v_pk_mul_f32 v[94:95], v[200:201], v[94:95]
	global_load_dwordx2 v[200:201], v212, s[52:53] offset:1024
	v_mul_f32_e32 v91, 0x3db504f3, v5
	v_add_f32_e32 v5, v94, v95
	v_mul_f32_e32 v191, 0x3db504f3, v5
	v_cvt_pk_bf16_f32 v5, v91, s0
	global_store_short v[122:123], v5, off offset:656
	v_cvt_pk_bf16_f32 v5, v191, s0
	global_store_short v[122:123], v5, off offset:784
	v_pk_mul_f32 v[90:91], v[26:27], v[90:91]
	v_pk_mul_f32 v[26:27], v[26:27], v[190:191]
	v_cvt_pk_bf16_f32 v5, v90, v91
	s_nop 0
	v_cvt_pk_bf16_f32 v122, v26, v27
	v_lshlrev_b32_e32 v27, 16, v186
	v_lshlrev_b32_e32 v26, 16, v185
	s_nop 0
	s_waitcnt vmcnt(27)
; DI bf16_t f2bf(float a) { return (bf16_t)(pack2(a, 0.f) & 0xffffu); }
; DI void post_z(const Params& p, int layer) {
;     ...
;       for (int i = 0; i < 32; ++i) {
;         bf16_t* p1 = zr + (size_t)i * ZS + colbase + lane;
;         float2 cs = rope[(spos + i) * 64 + lane];
;         float o1 = (x1[i] * cs.x - x2[i] * cs.y) * 0.08838834764831845f;
;         float o2 = (x1[i] * cs.y + x2[i] * cs.x) * 0.08838834764831845f;
;         p1[0] = f2bf(o1);
;         p1[64] = f2bf(o2);
;         float zeta = exp2f(lg2 * (float)(127 - ((spos + i) & 127)));
;         u1[i] = f2bf(o1 * zeta);
;         u2[i] = f2bf(o2 * zeta);
;       }
;       bf16_t* d1 = kzT + ((size_t)((b * 4 + h) * 128 + lane)) * TS + spos;
; #pragma unroll
;       for (int q4 = 0; q4 < 4; ++q4) {
;         *(uint4*)(d1 + q4 * 8) = make_uint4(u1[q4 * 8 + 0] | (u1[q4 * 8 + 1] << 16), u1[q4 * 8 + 2] | (u1[q4 * 8 + 3] << 16),
;                                             u1[q4 * 8 + 4] | (u1[q4 * 8 + 5] << 16), u1[q4 * 8 + 6] | (u1[q4 * 8 + 7] << 16));
;         *(uint4*)(d1 + (size_t)64 * TS + q4 * 8) = make_uint4(u2[q4 * 8 + 0] | (u2[q4 * 8 + 1] << 16), u2[q4 * 8 + 2] | (u2[q4 * 8 + 3] << 16),
;                                                               u2[q4 * 8 + 4] | (u2[q4 * 8 + 5] << 16), u2[q4 * 8 + 6] | (u2[q4 * 8 + 7] << 16));
	v_pk_mul_f32 v[94:95], v[202:203], v[26:27] op_sel:[0,1] op_sel_hi:[1,0]
	s_nop 0
	v_sub_f32_e32 v83, v94, v95
	v_pk_mul_f32 v[26:27], v[202:203], v[26:27]
	global_load_dwordx2 v[202:203], v212, s[52:53] offset:1536
	v_mul_f32_e32 v195, 0x3db504f3, v83
	v_add_f32_e32 v26, v26, v27
	v_mul_f32_e32 v83, 0x3db504f3, v26
	v_cvt_pk_bf16_f32 v26, v195, s0
	global_store_short v[120:121], v26, off offset:3264
	v_cvt_pk_bf16_f32 v26, v83, s0
	global_store_short v[120:121], v26, off offset:3392
	v_pk_mul_f32 v[26:27], v[2:3], v[194:195]
	v_pk_mul_f32 v[2:3], v[2:3], v[82:83]
	v_cvt_pk_bf16_f32 v90, v26, v27
	s_nop 0
	v_cvt_pk_bf16_f32 v91, v2, v3
	v_lshlrev_b32_e32 v3, 16, v184
	v_lshlrev_b32_e32 v2, 16, v183
	v_lshlrev_b32_e32 v95, 16, v182
	v_lshlrev_b32_e32 v94, 16, v181
	s_nop 0
	s_waitcnt vmcnt(29)
	v_pk_mul_f32 v[82:83], v[204:205], v[2:3]
	s_nop 0
	v_sub_f32_e32 v82, v82, v83
	v_pk_mul_f32 v[2:3], v[204:205], v[2:3] op_sel:[0,1] op_sel_hi:[1,0]
	global_load_dwordx2 v[204:205], v212, s[52:53] offset:2048
	v_mul_f32_e32 v82, 0x3db504f3, v82
	v_add_f32_e32 v83, v2, v3
	v_and_b32_e32 v2, 0xffff0000, v90
	v_lshlrev_b32_e32 v3, 16, v90
	v_or_b32_sdwa v27, v2, v5 dst_sel:DWORD dst_unused:UNUSED_PAD src0_sel:DWORD src1_sel:WORD_1
	v_cvt_pk_bf16_f32 v2, v82, s0
	v_or_b32_sdwa v26, v3, v5 dst_sel:DWORD dst_unused:UNUSED_PAD src0_sel:DWORD src1_sel:WORD_0
	global_store_short v[118:119], v2, off offset:1776
	v_and_b32_e32 v2, 0xffff0000, v91
	v_lshlrev_b32_e32 v5, 16, v91
	v_mul_f32_e32 v90, 0x3db504f3, v83
	v_or_b32_sdwa v3, v2, v122 dst_sel:DWORD dst_unused:UNUSED_PAD src0_sel:DWORD src1_sel:WORD_1
	v_or_b32_sdwa v2, v5, v122 dst_sel:DWORD dst_unused:UNUSED_PAD src0_sel:DWORD src1_sel:WORD_0
	v_cvt_pk_bf16_f32 v5, v90, s0
	global_store_short v[118:119], v5, off offset:1904
	s_nop 0
	s_nop 0
	s_waitcnt vmcnt(31)
	v_pk_mul_f32 v[120:121], v[206:207], v[94:95] op_sel:[0,1] op_sel_hi:[1,0]
	s_nop 0
	v_sub_f32_e32 v5, v120, v121
	v_pk_mul_f32 v[94:95], v[206:207], v[94:95]
	global_load_dwordx2 v[206:207], v212, s[52:53] offset:2560
	s_nop 0
	v_mul_f32_e32 v120, 0x3db504f3, v5
	v_add_f32_e32 v5, v94, v95
	v_mul_f32_e32 v94, 0x3db504f3, v5
	v_cvt_pk_bf16_f32 v5, v120, s0
	global_store_short v[116:117], v5, off offset:288
	v_cvt_pk_bf16_f32 v5, v94, s0
	global_store_short v[116:117], v5, off offset:416
	v_lshlrev_b32_e32 v117, 16, v180
	v_lshlrev_b32_e32 v116, 16, v179
	s_nop 0
	s_waitcnt vmcnt(33)
	v_pk_mul_f32 v[122:123], v[208:209], v[116:117] op_sel:[0,1] op_sel_hi:[1,0]
	s_nop 0
	v_sub_f32_e32 v5, v122, v123
	v_pk_mul_f32 v[116:117], v[208:209], v[116:117]
	global_load_dwordx2 v[208:209], v212, s[52:53] offset:3072
	v_mul_f32_e32 v83, 0x3db504f3, v5
	v_add_f32_e32 v5, v116, v117
	v_mul_f32_e32 v91, 0x3db504f3, v5
	v_cvt_pk_bf16_f32 v5, v83, s0
	global_store_short v[114:115], v5, off offset:2896
	v_cvt_pk_bf16_f32 v5, v91, s0
	global_store_short v[114:115], v5, off offset:3024
	s_nop 0
	v_pk_mul_f32 v[82:83], v[68:69], v[82:83]
	v_pk_mul_f32 v[68:69], v[68:69], v[90:91]
	v_cvt_pk_bf16_f32 v114, v82, v83
	v_cvt_pk_bf16_f32 v115, v68, v69
	v_lshlrev_b32_e32 v69, 16, v178
	v_lshlrev_b32_e32 v68, 16, v177
	s_nop 0
	s_waitcnt vmcnt(35)
	v_pk_mul_f32 v[82:83], v[210:211], v[68:69] op_sel:[0,1] op_sel_hi:[1,0]
	s_nop 0
	v_sub_f32_e32 v82, v82, v83
	v_pk_mul_f32 v[4:5], v[210:211], v[68:69]
	global_load_dwordx2 v[210:211], v212, s[52:53] offset:3584
	v_mul_f32_e32 v121, 0x3db504f3, v82
	v_add_f32_e32 v4, v4, v5
	v_add_co_u32_e32 v82, vcc, s5, v16
	v_mul_f32_e32 v95, 0x3db504f3, v4
	v_cvt_pk_bf16_f32 v4, v121, s0
	v_addc_co_u32_e32 v83, vcc, 0, v17, vcc
	s_movk_i32 s5, 0x2000
	global_store_short v[112:113], v4, off offset:1408
	v_cvt_pk_bf16_f32 v4, v95, s0
	v_add_co_u32_e32 v68, vcc, s5, v16
	global_store_short v[112:113], v4, off offset:1536
	v_pk_mul_f32 v[4:5], v[28:29], v[120:121]
	v_addc_co_u32_e32 v69, vcc, 0, v17, vcc
	v_cvt_pk_bf16_f32 v112, v4, v5
	v_pk_mul_f32 v[4:5], v[28:29], v[94:95]
	s_nop 0
	v_cvt_pk_bf16_f32 v94, v4, v5
	v_lshlrev_b32_e32 v5, 16, v176
	v_lshlrev_b32_e32 v4, 16, v175
	s_mov_b32 s5, 0x102000
	s_nop 0
	s_waitcnt vmcnt(37)
	v_pk_mul_f32 v[90:91], v[216:217], v[4:5]
	v_pk_mul_f32 v[4:5], v[216:217], v[4:5] op_sel:[0,1] op_sel_hi:[1,0]
	v_sub_f32_e32 v90, v90, v91
	v_add_f32_e32 v91, v4, v5
	v_and_b32_e32 v4, 0xffff0000, v112
	v_lshlrev_b32_e32 v5, 16, v112
	v_or_b32_sdwa v29, v4, v114 dst_sel:DWORD dst_unused:UNUSED_PAD src0_sel:DWORD src1_sel:WORD_1
	v_and_b32_e32 v4, 0xffff0000, v94
	v_lshlrev_b32_e32 v94, 16, v94
	v_mul_f32_e32 v90, 0x3db504f3, v90
	v_or_b32_sdwa v28, v5, v114 dst_sel:DWORD dst_unused:UNUSED_PAD src0_sel:DWORD src1_sel:WORD_0
	v_or_b32_sdwa v5, v4, v115 dst_sel:DWORD dst_unused:UNUSED_PAD src0_sel:DWORD src1_sel:WORD_1
	v_or_b32_sdwa v4, v94, v115 dst_sel:DWORD dst_unused:UNUSED_PAD src0_sel:DWORD src1_sel:WORD_0
	v_cvt_pk_bf16_f32 v94, v90, s0
	global_store_short v[110:111], v94, off offset:4016
	s_nop 0
	v_mul_f32_e32 v94, 0x3db504f3, v91
	v_cvt_pk_bf16_f32 v91, v94, s0
	global_store_short v[108:109], v91, off offset:48
	v_lshlrev_b32_e32 v109, 16, v173
	v_lshlrev_b32_e32 v108, 16, v172
	s_nop 0
	s_waitcnt vmcnt(38)
	v_pk_mul_f32 v[112:113], v[218:219], v[108:109] op_sel:[0,1] op_sel_hi:[1,0]
	s_nop 0
	v_sub_f32_e32 v91, v112, v113
	v_pk_mul_f32 v[108:109], v[218:219], v[108:109]
	s_nop 0
	v_mul_f32_e32 v112, 0x3db504f3, v91
	v_add_f32_e32 v91, v108, v109
	v_mul_f32_e32 v108, 0x3db504f3, v91
	v_cvt_pk_bf16_f32 v91, v112, s0
	global_store_short v[106:107], v91, off offset:2528
	v_cvt_pk_bf16_f32 v91, v108, s0
	global_store_short v[106:107], v91, off offset:2656
	v_lshlrev_b32_e32 v107, 16, v171
	v_lshlrev_b32_e32 v106, 16, v170
	s_nop 0
	s_waitcnt vmcnt(39)
; DI bf16_t f2bf(float a) { return (bf16_t)(pack2(a, 0.f) & 0xffffu); }
; DI void post_z(const Params& p, int layer) {
;     ...
;       for (int i = 0; i < 32; ++i) {
;         bf16_t* p1 = zr + (size_t)i * ZS + colbase + lane;
;         float2 cs = rope[(spos + i) * 64 + lane];
;         float o1 = (x1[i] * cs.x - x2[i] * cs.y) * 0.08838834764831845f;
;         float o2 = (x1[i] * cs.y + x2[i] * cs.x) * 0.08838834764831845f;
;         p1[0] = f2bf(o1);
;         p1[64] = f2bf(o2);
;         float zeta = exp2f(lg2 * (float)(127 - ((spos + i) & 127)));
;         u1[i] = f2bf(o1 * zeta);
;         u2[i] = f2bf(o2 * zeta);
;       }
;       bf16_t* d1 = kzT + ((size_t)((b * 4 + h) * 128 + lane)) * TS + spos;
; #pragma unroll
;       for (int q4 = 0; q4 < 4; ++q4) {
;         *(uint4*)(d1 + q4 * 8) = make_uint4(u1[q4 * 8 + 0] | (u1[q4 * 8 + 1] << 16), u1[q4 * 8 + 2] | (u1[q4 * 8 + 3] << 16),
;                                             u1[q4 * 8 + 4] | (u1[q4 * 8 + 5] << 16), u1[q4 * 8 + 6] | (u1[q4 * 8 + 7] << 16));
;         *(uint4*)(d1 + (size_t)64 * TS + q4 * 8) = make_uint4(u2[q4 * 8 + 0] | (u2[q4 * 8 + 1] << 16), u2[q4 * 8 + 2] | (u2[q4 * 8 + 3] << 16),
;                                                               u2[q4 * 8 + 4] | (u2[q4 * 8 + 5] << 16), u2[q4 * 8 + 6] | (u2[q4 * 8 + 7] << 16));
	v_pk_mul_f32 v[114:115], v[220:221], v[106:107] op_sel:[0,1] op_sel_hi:[1,0]
	s_nop 0
	v_sub_f32_e32 v91, v114, v115
	v_pk_mul_f32 v[106:107], v[220:221], v[106:107]
	v_mul_f32_e32 v91, 0x3db504f3, v91
	v_add_f32_e32 v95, v106, v107
	v_mul_f32_e32 v95, 0x3db504f3, v95
	v_cvt_pk_bf16_f32 v106, v91, s0
	global_store_short v[104:105], v106, off offset:1040
	v_cvt_pk_bf16_f32 v106, v95, s0
	global_store_short v[104:105], v106, off offset:1168
	v_pk_mul_f32 v[90:91], v[10:11], v[90:91]
	v_pk_mul_f32 v[10:11], v[10:11], v[94:95]
	v_cvt_pk_bf16_f32 v104, v90, v91
	s_nop 0
	v_cvt_pk_bf16_f32 v105, v10, v11
	v_lshlrev_b32_e32 v11, 16, v169
	v_lshlrev_b32_e32 v10, 16, v168
	s_nop 0
	s_waitcnt vmcnt(40)
	v_pk_mul_f32 v[94:95], v[222:223], v[10:11] op_sel:[0,1] op_sel_hi:[1,0]
	s_nop 0
	v_sub_f32_e32 v94, v94, v95
	v_pk_mul_f32 v[10:11], v[222:223], v[10:11]
	v_mul_f32_e32 v113, 0x3db504f3, v94
	v_add_f32_e32 v10, v10, v11
	v_mul_f32_e32 v109, 0x3db504f3, v10
	v_cvt_pk_bf16_f32 v10, v113, s0
	global_store_short v[102:103], v10, off offset:3648
	v_cvt_pk_bf16_f32 v10, v109, s0
	global_store_short v[102:103], v10, off offset:3776
	v_pk_mul_f32 v[10:11], v[6:7], v[112:113]
	v_pk_mul_f32 v[6:7], v[6:7], v[108:109]
	v_cvt_pk_bf16_f32 v94, v10, v11
	s_nop 0
	v_cvt_pk_bf16_f32 v95, v6, v7
	v_lshlrev_b32_e32 v7, 16, v167
	v_lshlrev_b32_e32 v6, 16, v166
	s_nop 0
	s_nop 0
	s_waitcnt vmcnt(41)
	v_pk_mul_f32 v[90:91], v[224:225], v[6:7]
	s_nop 0
	v_sub_f32_e32 v90, v90, v91
	v_pk_mul_f32 v[6:7], v[224:225], v[6:7] op_sel:[0,1] op_sel_hi:[1,0]
	v_lshlrev_b32_e32 v10, 16, v94
	v_add_f32_e32 v91, v6, v7
	v_and_b32_e32 v6, 0xffff0000, v94
	v_mul_f32_e32 v90, 0x3db504f3, v90
	v_or_b32_sdwa v7, v6, v104 dst_sel:DWORD dst_unused:UNUSED_PAD src0_sel:DWORD src1_sel:WORD_1
	v_or_b32_sdwa v6, v10, v104 dst_sel:DWORD dst_unused:UNUSED_PAD src0_sel:DWORD src1_sel:WORD_0
	v_cvt_pk_bf16_f32 v10, v90, s0
	global_store_short v[100:101], v10, off offset:2160
	v_and_b32_e32 v10, 0xffff0000, v95
	v_lshlrev_b32_e32 v94, 16, v95
	v_or_b32_sdwa v11, v10, v105 dst_sel:DWORD dst_unused:UNUSED_PAD src0_sel:DWORD src1_sel:WORD_1
	v_or_b32_sdwa v10, v94, v105 dst_sel:DWORD dst_unused:UNUSED_PAD src0_sel:DWORD src1_sel:WORD_0
	v_mul_f32_e32 v94, 0x3db504f3, v91
	v_cvt_pk_bf16_f32 v91, v94, s0
	global_store_short v[100:101], v91, off offset:2288
	v_lshlrev_b32_e32 v101, 16, v165
	v_lshlrev_b32_e32 v100, 16, v164
	s_nop 0
	s_waitcnt vmcnt(42)
	v_pk_mul_f32 v[104:105], v[226:227], v[100:101] op_sel:[0,1] op_sel_hi:[1,0]
	s_nop 0
	v_sub_f32_e32 v91, v104, v105
	v_pk_mul_f32 v[100:101], v[226:227], v[100:101]
	s_nop 0
	v_mul_f32_e32 v104, 0x3db504f3, v91
	v_add_f32_e32 v91, v100, v101
	v_mul_f32_e32 v100, 0x3db504f3, v91
	v_cvt_pk_bf16_f32 v91, v104, s0
	global_store_short v[98:99], v91, off offset:672
	v_cvt_pk_bf16_f32 v91, v100, s0
	global_store_short v[98:99], v91, off offset:800
	v_lshlrev_b32_e32 v99, 16, v163
	v_lshlrev_b32_e32 v98, 16, v161
	s_nop 0
	s_nop 0
	s_waitcnt vmcnt(43)
	v_pk_mul_f32 v[106:107], v[228:229], v[98:99] op_sel:[0,1] op_sel_hi:[1,0]
	s_nop 0
	v_sub_f32_e32 v91, v106, v107
	v_pk_mul_f32 v[98:99], v[228:229], v[98:99]
	v_mul_f32_e32 v91, 0x3db504f3, v91
	v_add_f32_e32 v95, v98, v99
	v_mul_f32_e32 v95, 0x3db504f3, v95
	v_cvt_pk_bf16_f32 v98, v91, s0
	global_store_short v[96:97], v98, off offset:3280
	v_cvt_pk_bf16_f32 v98, v95, s0
	global_store_short v[96:97], v98, off offset:3408
	v_pk_mul_f32 v[90:91], v[12:13], v[90:91]
	v_pk_mul_f32 v[12:13], v[12:13], v[94:95]
	v_cvt_pk_bf16_f32 v96, v90, v91
	v_cvt_pk_bf16_f32 v94, v12, v13
	v_lshlrev_b32_e32 v13, 16, v160
	v_lshlrev_b32_e32 v12, 16, v159
	s_nop 0
	s_waitcnt vmcnt(44)
	v_pk_mul_f32 v[90:91], v[230:231], v[12:13] op_sel:[0,1] op_sel_hi:[1,0]
	s_nop 0
	v_sub_f32_e32 v90, v90, v91
	v_pk_mul_f32 v[12:13], v[230:231], v[12:13]
	v_mul_f32_e32 v105, 0x3db504f3, v90
	v_add_f32_e32 v12, v12, v13
	v_mul_f32_e32 v101, 0x3db504f3, v12
	v_cvt_pk_bf16_f32 v12, v105, s0
	global_store_short v[92:93], v12, off offset:1792
	v_cvt_pk_bf16_f32 v12, v101, s0
	global_store_short v[92:93], v12, off offset:1920
	v_pk_mul_f32 v[12:13], v[8:9], v[104:105]
	v_pk_mul_f32 v[8:9], v[8:9], v[100:101]
	v_cvt_pk_bf16_f32 v90, v12, v13
	s_nop 0
	v_cvt_pk_bf16_f32 v91, v8, v9
	v_lshlrev_b32_e32 v9, 16, v157
	v_lshlrev_b32_e32 v8, 16, v156
	s_nop 0
	s_nop 0
	s_waitcnt vmcnt(45)
	v_pk_mul_f32 v[82:83], v[232:233], v[8:9]
	v_pk_mul_f32 v[8:9], v[232:233], v[8:9] op_sel:[0,1] op_sel_hi:[1,0]
	v_sub_f32_e32 v82, v82, v83
	v_add_f32_e32 v83, v8, v9
	v_and_b32_e32 v8, 0xffff0000, v90
	v_lshlrev_b32_e32 v12, 16, v90
	v_or_b32_sdwa v9, v8, v96 dst_sel:DWORD dst_unused:UNUSED_PAD src0_sel:DWORD src1_sel:WORD_1
	v_or_b32_sdwa v8, v12, v96 dst_sel:DWORD dst_unused:UNUSED_PAD src0_sel:DWORD src1_sel:WORD_0
	v_and_b32_e32 v12, 0xffff0000, v91
	v_lshlrev_b32_e32 v90, 16, v91
	v_mul_f32_e32 v82, 0x3db504f3, v82
	v_or_b32_sdwa v13, v12, v94 dst_sel:DWORD dst_unused:UNUSED_PAD src0_sel:DWORD src1_sel:WORD_1
	v_or_b32_sdwa v12, v90, v94 dst_sel:DWORD dst_unused:UNUSED_PAD src0_sel:DWORD src1_sel:WORD_0
	v_cvt_pk_bf16_f32 v90, v82, s0
	global_store_short v[88:89], v90, off offset:304
	v_mul_f32_e32 v90, 0x3db504f3, v83
	v_cvt_pk_bf16_f32 v83, v90, s0
	global_store_short v[88:89], v83, off offset:432
	v_lshlrev_b32_e32 v89, 16, v155
	v_lshlrev_b32_e32 v88, 16, v154
	s_nop 0
	s_waitcnt vmcnt(46)
	v_pk_mul_f32 v[94:95], v[234:235], v[88:89] op_sel:[0,1] op_sel_hi:[1,0]
	s_nop 0
	v_sub_f32_e32 v83, v94, v95
	v_pk_mul_f32 v[88:89], v[234:235], v[88:89]
	s_nop 0
	v_mul_f32_e32 v94, 0x3db504f3, v83
	v_add_f32_e32 v83, v88, v89
	v_mul_f32_e32 v88, 0x3db504f3, v83
	v_cvt_pk_bf16_f32 v83, v94, s0
	global_store_short v[86:87], v83, off offset:2912
	v_cvt_pk_bf16_f32 v83, v88, s0
	global_store_short v[86:87], v83, off offset:3040
	v_lshlrev_b32_e32 v87, 16, v153
	v_lshlrev_b32_e32 v86, 16, v152
	s_nop 0
	s_waitcnt vmcnt(47)
; DI bf16_t f2bf(float a) { return (bf16_t)(pack2(a, 0.f) & 0xffffu); }
; DI void post_z(const Params& p, int layer) {
;     ...
;       for (int i = 0; i < 32; ++i) {
;         bf16_t* p1 = zr + (size_t)i * ZS + colbase + lane;
;         float2 cs = rope[(spos + i) * 64 + lane];
;         float o1 = (x1[i] * cs.x - x2[i] * cs.y) * 0.08838834764831845f;
;         float o2 = (x1[i] * cs.y + x2[i] * cs.x) * 0.08838834764831845f;
;         p1[0] = f2bf(o1);
;         p1[64] = f2bf(o2);
;         float zeta = exp2f(lg2 * (float)(127 - ((spos + i) & 127)));
;         u1[i] = f2bf(o1 * zeta);
;         u2[i] = f2bf(o2 * zeta);
;       }
;       bf16_t* d1 = kzT + ((size_t)((b * 4 + h) * 128 + lane)) * TS + spos;
; #pragma unroll
;       for (int q4 = 0; q4 < 4; ++q4) {
;         *(uint4*)(d1 + q4 * 8) = make_uint4(u1[q4 * 8 + 0] | (u1[q4 * 8 + 1] << 16), u1[q4 * 8 + 2] | (u1[q4 * 8 + 3] << 16),
;                                             u1[q4 * 8 + 4] | (u1[q4 * 8 + 5] << 16), u1[q4 * 8 + 6] | (u1[q4 * 8 + 7] << 16));
;         *(uint4*)(d1 + (size_t)64 * TS + q4 * 8) = make_uint4(u2[q4 * 8 + 0] | (u2[q4 * 8 + 1] << 16), u2[q4 * 8 + 2] | (u2[q4 * 8 + 3] << 16),
;                                                               u2[q4 * 8 + 4] | (u2[q4 * 8 + 5] << 16), u2[q4 * 8 + 6] | (u2[q4 * 8 + 7] << 16));
	v_pk_mul_f32 v[96:97], v[236:237], v[86:87] op_sel:[0,1] op_sel_hi:[1,0]
	s_nop 0
	v_sub_f32_e32 v83, v96, v97
	v_pk_mul_f32 v[86:87], v[236:237], v[86:87]
	v_mul_f32_e32 v83, 0x3db504f3, v83
	v_add_f32_e32 v86, v86, v87
	v_mul_f32_e32 v91, 0x3db504f3, v86
	v_cvt_pk_bf16_f32 v86, v83, s0
	global_store_short v[84:85], v86, off offset:1424
	v_cvt_pk_bf16_f32 v86, v91, s0
	global_store_short v[84:85], v86, off offset:1552
	v_pk_mul_f32 v[82:83], v[18:19], v[82:83]
	v_pk_mul_f32 v[18:19], v[18:19], v[90:91]
	v_cvt_pk_bf16_f32 v86, v82, v83
	s_nop 0
	v_cvt_pk_bf16_f32 v87, v18, v19
	v_lshlrev_b32_e32 v19, 16, v151
	v_lshlrev_b32_e32 v18, 16, v150
	s_nop 0
	s_waitcnt vmcnt(48)
	v_pk_mul_f32 v[84:85], v[238:239], v[18:19] op_sel:[0,1] op_sel_hi:[1,0]
	s_nop 0
	v_sub_f32_e32 v84, v84, v85
	v_pk_mul_f32 v[18:19], v[238:239], v[18:19]
	v_mul_f32_e32 v95, 0x3db504f3, v84
	v_add_f32_e32 v18, v18, v19
	v_mul_f32_e32 v89, 0x3db504f3, v18
	v_cvt_pk_bf16_f32 v18, v95, s0
	global_store_short v[80:81], v18, off offset:4032
	v_cvt_pk_bf16_f32 v18, v89, s0
	global_store_short v[78:79], v18, off offset:64
	v_pk_mul_f32 v[18:19], v[14:15], v[94:95]
	v_pk_mul_f32 v[14:15], v[14:15], v[88:89]
	v_cvt_pk_bf16_f32 v80, v18, v19
	s_nop 0
	v_cvt_pk_bf16_f32 v81, v14, v15
	v_lshlrev_b32_e32 v15, 16, v149
	v_lshlrev_b32_e32 v14, 16, v148
	s_nop 0
	s_nop 0
	s_waitcnt vmcnt(49)
	v_pk_mul_f32 v[78:79], v[240:241], v[14:15]
	s_nop 0
	v_sub_f32_e32 v78, v78, v79
	v_pk_mul_f32 v[14:15], v[240:241], v[14:15] op_sel:[0,1] op_sel_hi:[1,0]
	v_lshlrev_b32_e32 v18, 16, v80
	v_add_f32_e32 v79, v14, v15
	v_and_b32_e32 v14, 0xffff0000, v80
	v_mul_f32_e32 v78, 0x3db504f3, v78
	v_or_b32_sdwa v15, v14, v86 dst_sel:DWORD dst_unused:UNUSED_PAD src0_sel:DWORD src1_sel:WORD_1
	v_or_b32_sdwa v14, v18, v86 dst_sel:DWORD dst_unused:UNUSED_PAD src0_sel:DWORD src1_sel:WORD_0
	v_cvt_pk_bf16_f32 v18, v78, s0
	global_store_short v[76:77], v18, off offset:2544
	v_and_b32_e32 v18, 0xffff0000, v81
	v_lshlrev_b32_e32 v80, 16, v81
	v_or_b32_sdwa v19, v18, v87 dst_sel:DWORD dst_unused:UNUSED_PAD src0_sel:DWORD src1_sel:WORD_1
	v_or_b32_sdwa v18, v80, v87 dst_sel:DWORD dst_unused:UNUSED_PAD src0_sel:DWORD src1_sel:WORD_0
	v_mul_f32_e32 v80, 0x3db504f3, v79
	v_cvt_pk_bf16_f32 v79, v80, s0
	global_store_short v[76:77], v79, off offset:2672
	v_lshlrev_b32_e32 v77, 16, v147
	v_lshlrev_b32_e32 v76, 16, v146
	s_nop 0
	s_waitcnt vmcnt(50)
	v_pk_mul_f32 v[84:85], v[242:243], v[76:77] op_sel:[0,1] op_sel_hi:[1,0]
	s_nop 0
	v_sub_f32_e32 v79, v84, v85
	v_pk_mul_f32 v[76:77], v[242:243], v[76:77]
	s_nop 0
	v_mul_f32_e32 v84, 0x3db504f3, v79
	v_add_f32_e32 v76, v76, v77
	v_mul_f32_e32 v76, 0x3db504f3, v76
	v_cvt_pk_bf16_f32 v77, v84, s0
	global_store_short v[74:75], v77, off offset:1056
	v_cvt_pk_bf16_f32 v77, v76, s0
	global_store_short v[74:75], v77, off offset:1184
	v_lshlrev_b32_e32 v75, 16, v145
	v_lshlrev_b32_e32 v74, 16, v144
	s_nop 0
	s_nop 0
	s_waitcnt vmcnt(51)
	v_pk_mul_f32 v[86:87], v[244:245], v[74:75] op_sel:[0,1] op_sel_hi:[1,0]
	s_nop 0
	v_sub_f32_e32 v77, v86, v87
	v_pk_mul_f32 v[74:75], v[244:245], v[74:75]
	v_mul_f32_e32 v79, 0x3db504f3, v77
	v_add_f32_e32 v74, v74, v75
	v_mul_f32_e32 v81, 0x3db504f3, v74
	v_cvt_pk_bf16_f32 v74, v79, s0
	global_store_short v[72:73], v74, off offset:3664
	v_cvt_pk_bf16_f32 v74, v81, s0
	global_store_short v[72:73], v74, off offset:3792
	v_pk_mul_f32 v[72:73], v[48:49], v[78:79]
	v_pk_mul_f32 v[48:49], v[48:49], v[80:81]
	v_cvt_pk_bf16_f32 v74, v72, v73
	v_cvt_pk_bf16_f32 v75, v48, v49
	v_lshlrev_b32_e32 v49, 16, v143
	v_lshlrev_b32_e32 v48, 16, v142
	s_nop 0
	s_waitcnt vmcnt(52)
	v_pk_mul_f32 v[72:73], v[246:247], v[48:49] op_sel:[0,1] op_sel_hi:[1,0]
	s_nop 0
	v_sub_f32_e32 v72, v72, v73
	v_pk_mul_f32 v[48:49], v[246:247], v[48:49]
	v_mul_f32_e32 v85, 0x3db504f3, v72
	v_add_f32_e32 v48, v48, v49
	v_mul_f32_e32 v77, 0x3db504f3, v48
	v_cvt_pk_bf16_f32 v48, v85, s0
	global_store_short v[70:71], v48, off offset:2176
	v_cvt_pk_bf16_f32 v48, v77, s0
	global_store_short v[70:71], v48, off offset:2304
	v_pk_mul_f32 v[48:49], v[20:21], v[84:85]
	v_pk_mul_f32 v[20:21], v[20:21], v[76:77]
	v_cvt_pk_bf16_f32 v70, v48, v49
	v_add_co_u32_e32 v48, vcc, s12, v16
	v_cvt_pk_bf16_f32 v71, v20, v21
	s_nop 0
	v_addc_co_u32_e32 v49, vcc, 0, v17, vcc
	s_nop 0
	v_lshlrev_b32_e32 v21, 16, v141
	v_lshlrev_b32_e32 v20, 16, v140
	s_nop 0
	s_nop 0
	s_waitcnt vmcnt(53)
	v_pk_mul_f32 v[68:69], v[248:249], v[20:21]
	v_pk_mul_f32 v[16:17], v[248:249], v[20:21] op_sel:[0,1] op_sel_hi:[1,0]
	v_sub_f32_e32 v68, v68, v69
	v_add_f32_e32 v69, v16, v17
	v_and_b32_e32 v16, 0xffff0000, v70
	v_lshlrev_b32_e32 v20, 16, v70
	v_or_b32_sdwa v17, v16, v74 dst_sel:DWORD dst_unused:UNUSED_PAD src0_sel:DWORD src1_sel:WORD_1
	v_or_b32_sdwa v16, v20, v74 dst_sel:DWORD dst_unused:UNUSED_PAD src0_sel:DWORD src1_sel:WORD_0
	v_and_b32_e32 v20, 0xffff0000, v71
	v_lshlrev_b32_e32 v70, 16, v71
	v_mul_f32_e32 v68, 0x3db504f3, v68
	v_or_b32_sdwa v21, v20, v75 dst_sel:DWORD dst_unused:UNUSED_PAD src0_sel:DWORD src1_sel:WORD_1
	v_or_b32_sdwa v20, v70, v75 dst_sel:DWORD dst_unused:UNUSED_PAD src0_sel:DWORD src1_sel:WORD_0
	v_cvt_pk_bf16_f32 v70, v68, s0
	global_store_short v[66:67], v70, off offset:688
	v_mul_f32_e32 v70, 0x3db504f3, v69
	v_cvt_pk_bf16_f32 v69, v70, s0
	global_store_short v[66:67], v69, off offset:816
	v_lshlrev_b32_e32 v67, 16, v139
	v_lshlrev_b32_e32 v66, 16, v138
	s_nop 0
	s_waitcnt vmcnt(54)
; DI bf16_t f2bf(float a) { return (bf16_t)(pack2(a, 0.f) & 0xffffu); }
; DI void post_z(const Params& p, int layer) {
;     ...
;       for (int i = 0; i < 32; ++i) {
;         bf16_t* p1 = zr + (size_t)i * ZS + colbase + lane;
;         float2 cs = rope[(spos + i) * 64 + lane];
;         float o1 = (x1[i] * cs.x - x2[i] * cs.y) * 0.08838834764831845f;
;         float o2 = (x1[i] * cs.y + x2[i] * cs.x) * 0.08838834764831845f;
;         p1[0] = f2bf(o1);
;         p1[64] = f2bf(o2);
;         float zeta = exp2f(lg2 * (float)(127 - ((spos + i) & 127)));
;         u1[i] = f2bf(o1 * zeta);
;         u2[i] = f2bf(o2 * zeta);
;       }
;       bf16_t* d1 = kzT + ((size_t)((b * 4 + h) * 128 + lane)) * TS + spos;
; #pragma unroll
;       for (int q4 = 0; q4 < 4; ++q4) {
;         *(uint4*)(d1 + q4 * 8) = make_uint4(u1[q4 * 8 + 0] | (u1[q4 * 8 + 1] << 16), u1[q4 * 8 + 2] | (u1[q4 * 8 + 3] << 16),
;                                             u1[q4 * 8 + 4] | (u1[q4 * 8 + 5] << 16), u1[q4 * 8 + 6] | (u1[q4 * 8 + 7] << 16));
;         *(uint4*)(d1 + (size_t)64 * TS + q4 * 8) = make_uint4(u2[q4 * 8 + 0] | (u2[q4 * 8 + 1] << 16), u2[q4 * 8 + 2] | (u2[q4 * 8 + 3] << 16),
;                                                               u2[q4 * 8 + 4] | (u2[q4 * 8 + 5] << 16), u2[q4 * 8 + 6] | (u2[q4 * 8 + 7] << 16));
;       }
	v_pk_mul_f32 v[74:75], v[198:199], v[66:67] op_sel:[0,1] op_sel_hi:[1,0]
	s_nop 0
	v_sub_f32_e32 v69, v74, v75
	v_pk_mul_f32 v[66:67], v[198:199], v[66:67]
	s_nop 0
	v_mul_f32_e32 v74, 0x3db504f3, v69
	v_add_f32_e32 v66, v66, v67
	v_mul_f32_e32 v66, 0x3db504f3, v66
	v_cvt_pk_bf16_f32 v67, v74, s0
	global_store_short v[64:65], v67, off offset:3296
	v_cvt_pk_bf16_f32 v67, v66, s0
	global_store_short v[64:65], v67, off offset:3424
	v_lshlrev_b32_e32 v65, 16, v137
	v_lshlrev_b32_e32 v64, 16, v136
	s_nop 0
	s_waitcnt vmcnt(53)
	v_pk_mul_f32 v[76:77], v[200:201], v[64:65] op_sel:[0,1] op_sel_hi:[1,0]
	s_nop 0
	v_sub_f32_e32 v67, v76, v77
	v_pk_mul_f32 v[64:65], v[200:201], v[64:65]
	v_mul_f32_e32 v69, 0x3db504f3, v67
	v_add_f32_e32 v64, v64, v65
	v_mul_f32_e32 v71, 0x3db504f3, v64
	v_cvt_pk_bf16_f32 v64, v69, s0
	global_store_short v[62:63], v64, off offset:1808
	v_cvt_pk_bf16_f32 v64, v71, s0
	global_store_short v[62:63], v64, off offset:1936
	v_pk_mul_f32 v[62:63], v[24:25], v[68:69]
	v_pk_mul_f32 v[24:25], v[24:25], v[70:71]
	v_cvt_pk_bf16_f32 v68, v62, v63
	s_nop 0
	v_cvt_pk_bf16_f32 v69, v24, v25
	v_lshlrev_b32_e32 v25, 16, v135
	v_lshlrev_b32_e32 v24, 16, v134
	s_nop 0
	s_waitcnt vmcnt(52)
	v_pk_mul_f32 v[64:65], v[202:203], v[24:25] op_sel:[0,1] op_sel_hi:[1,0]
	s_nop 0
	v_sub_f32_e32 v64, v64, v65
	v_pk_mul_f32 v[24:25], v[202:203], v[24:25]
	v_mul_f32_e32 v75, 0x3db504f3, v64
	v_add_f32_e32 v24, v24, v25
	v_mul_f32_e32 v67, 0x3db504f3, v24
	v_cvt_pk_bf16_f32 v24, v75, s0
	global_store_short v[60:61], v24, off offset:320
	v_cvt_pk_bf16_f32 v24, v67, s0
	global_store_short v[60:61], v24, off offset:448
	v_pk_mul_f32 v[24:25], v[22:23], v[74:75]
	v_pk_mul_f32 v[22:23], v[22:23], v[66:67]
	v_cvt_pk_bf16_f32 v62, v24, v25
	s_nop 0
	v_cvt_pk_bf16_f32 v63, v22, v23
	v_lshlrev_b32_e32 v23, 16, v133
	v_lshlrev_b32_e32 v22, 16, v132
	s_nop 0
	s_nop 0
	s_waitcnt vmcnt(51)
	v_pk_mul_f32 v[60:61], v[204:205], v[22:23]
	s_nop 0
	v_sub_f32_e32 v60, v60, v61
	v_pk_mul_f32 v[22:23], v[204:205], v[22:23] op_sel:[0,1] op_sel_hi:[1,0]
	v_mul_f32_e32 v60, 0x3db504f3, v60
	v_add_f32_e32 v61, v22, v23
	v_and_b32_e32 v22, 0xffff0000, v62
	v_or_b32_sdwa v25, v22, v68 dst_sel:DWORD dst_unused:UNUSED_PAD src0_sel:DWORD src1_sel:WORD_1
	v_cvt_pk_bf16_f32 v22, v60, s0
	v_lshlrev_b32_e32 v23, 16, v62
	global_store_short v[58:59], v22, off offset:2928
	v_and_b32_e32 v22, 0xffff0000, v63
	v_lshlrev_b32_e32 v62, 16, v63
	v_or_b32_sdwa v24, v23, v68 dst_sel:DWORD dst_unused:UNUSED_PAD src0_sel:DWORD src1_sel:WORD_0
	v_or_b32_sdwa v23, v22, v69 dst_sel:DWORD dst_unused:UNUSED_PAD src0_sel:DWORD src1_sel:WORD_1
	v_or_b32_sdwa v22, v62, v69 dst_sel:DWORD dst_unused:UNUSED_PAD src0_sel:DWORD src1_sel:WORD_0
	v_mul_f32_e32 v62, 0x3db504f3, v61
	v_cvt_pk_bf16_f32 v61, v62, s0
	global_store_short v[58:59], v61, off offset:3056
	v_lshlrev_b32_e32 v59, 16, v131
	v_lshlrev_b32_e32 v58, 16, v130
	s_nop 0
	s_waitcnt vmcnt(50)
	v_pk_mul_f32 v[66:67], v[206:207], v[58:59] op_sel:[0,1] op_sel_hi:[1,0]
	s_nop 0
	v_sub_f32_e32 v61, v66, v67
	v_pk_mul_f32 v[58:59], v[206:207], v[58:59]
	s_nop 0
	v_mul_f32_e32 v66, 0x3db504f3, v61
	v_add_f32_e32 v58, v58, v59
	v_mul_f32_e32 v58, 0x3db504f3, v58
	v_cvt_pk_bf16_f32 v59, v66, s0
	global_store_short v[56:57], v59, off offset:1440
	v_cvt_pk_bf16_f32 v59, v58, s0
	global_store_short v[56:57], v59, off offset:1568
	v_lshlrev_b32_e32 v57, 16, v129
	v_lshlrev_b32_e32 v56, 16, v128
	s_nop 0
	s_nop 0
	s_waitcnt vmcnt(49)
	v_pk_mul_f32 v[68:69], v[208:209], v[56:57] op_sel:[0,1] op_sel_hi:[1,0]
	s_nop 0
	v_sub_f32_e32 v59, v68, v69
	v_pk_mul_f32 v[56:57], v[208:209], v[56:57]
	v_mul_f32_e32 v61, 0x3db504f3, v59
	v_add_f32_e32 v56, v56, v57
	v_mul_f32_e32 v63, 0x3db504f3, v56
	v_cvt_pk_bf16_f32 v56, v61, s0
	global_store_short v[54:55], v56, off offset:4048
	v_cvt_pk_bf16_f32 v54, v63, s0
	global_store_short v[52:53], v54, off offset:80
	v_lshlrev_b32_e32 v55, 16, v127
	v_lshlrev_b32_e32 v54, 16, v0
	v_pk_mul_f32 v[52:53], v[46:47], v[60:61]
	v_pk_mul_f32 v[46:47], v[46:47], v[62:63]
	v_cvt_pk_bf16_f32 v52, v52, v53
	v_cvt_pk_bf16_f32 v46, v46, v47
	s_nop 0
	s_waitcnt vmcnt(48)
	v_pk_mul_f32 v[56:57], v[210:211], v[54:55] op_sel:[0,1] op_sel_hi:[1,0]
	s_nop 0
	v_sub_f32_e32 v0, v56, v57
	v_pk_mul_f32 v[48:49], v[210:211], v[54:55]
	v_mul_f32_e32 v67, 0x3db504f3, v0
	v_add_f32_e32 v0, v48, v49
	v_mul_f32_e32 v59, 0x3db504f3, v0
	v_cvt_pk_bf16_f32 v0, v67, s0
	global_store_short v[50:51], v0, off offset:2560
	v_cvt_pk_bf16_f32 v0, v59, s0
	global_store_short v[50:51], v0, off offset:2688
	v_pk_mul_f32 v[48:49], v[44:45], v[66:67]
	global_store_dwordx4 v[42:43], v[26:29], off
	v_cvt_pk_bf16_f32 v47, v48, v49
	v_pk_mul_f32 v[44:45], v[44:45], v[58:59]
	v_add_co_u32_e32 v28, vcc, s5, v42
	v_cvt_pk_bf16_f32 v0, v44, v45
	s_nop 0
	v_addc_co_u32_e32 v29, vcc, 0, v43, vcc
	global_store_dwordx4 v[28:29], v[2:5], off
	global_store_dwordx4 v[42:43], v[6:9], off offset:16
	global_store_dwordx4 v[28:29], v[10:13], off offset:16
	global_store_dwordx4 v[42:43], v[14:17], off offset:32
	global_store_dwordx4 v[28:29], v[18:21], off offset:32
	v_and_b32_e32 v2, 0xffff0000, v47
	v_lshlrev_b32_e32 v3, 16, v47
	v_or_b32_sdwa v27, v2, v52 dst_sel:DWORD dst_unused:UNUSED_PAD src0_sel:DWORD src1_sel:WORD_1
	v_or_b32_sdwa v26, v3, v52 dst_sel:DWORD dst_unused:UNUSED_PAD src0_sel:DWORD src1_sel:WORD_0
	v_and_b32_e32 v2, 0xffff0000, v0
	v_lshlrev_b32_e32 v0, 16, v0
	global_store_dwordx4 v[42:43], v[24:27], off offset:48
	s_nop 1
	v_or_b32_sdwa v25, v2, v46 dst_sel:DWORD dst_unused:UNUSED_PAD src0_sel:DWORD src1_sel:WORD_1
	v_or_b32_sdwa v24, v0, v46 dst_sel:DWORD dst_unused:UNUSED_PAD src0_sel:DWORD src1_sel:WORD_0
	global_store_dwordx4 v[28:29], v[22:25], off offset:48
